# v057 + RG-LRU tile-top LDS fill: vmcnt counts relaxed by 3 for tiles>=1 so the fill no longer waits for the previous tile's Y-store acks
# baseline (speedup 1.0000x reference)
; #define LAS __attribute__((address_space(3)))
; DI void phase_rglru(const Params& p, unsigned char* shm) {
;     ...
;             __syncthreads();
; #pragma unroll
;             for (int j = 0; j < 3; ++j) { *(LAS u32x4*)(lds + XR + 3 * TR + loff[j]) = rx[j]; *(LAS u32x4*)(lds + GT + loff[j]) = rg[j]; }
;             if (tile < 31) {
;                 const size_t nb = base + (size_t)(tile + 1) * 64 * 1536;
; #pragma unroll
;                 for (int j = 0; j < 3; ++j) { rx[j] = *(const u32x4*)(XRg + nb + goff[j]); rg[j] = *(const u32x4*)(Gg + nb + goff[j]); }
;             }
.LBB0_843:
	s_cmp_eq_u32 s64, 31
	s_mul_i32 s10, s64, 0x18000
	s_waitcnt lgkmcnt(0)
	s_barrier
	s_cmp_eq_u32 s64, 0
	s_cbranch_scc1 .Lfill_first
	s_waitcnt vmcnt(8)
	ds_write_b128 v201, v[96:99] offset:1200
	s_waitcnt vmcnt(7)
	ds_write_b128 v201, v[100:103] offset:52480
	s_waitcnt vmcnt(6)
	ds_write_b128 v202, v[104:107] offset:1200
	s_waitcnt vmcnt(5)
	ds_write_b128 v202, v[108:111] offset:52480
	s_waitcnt vmcnt(4)
	ds_write_b128 v203, v[112:115] offset:1200
	s_waitcnt vmcnt(3)
	ds_write_b128 v203, v[116:119] offset:52480
	s_branch .Lfill_done
.Lfill_first:
	s_waitcnt vmcnt(5)
	ds_write_b128 v201, v[96:99] offset:1200
	s_waitcnt vmcnt(4)
	ds_write_b128 v201, v[100:103] offset:52480
	s_waitcnt vmcnt(3)
	ds_write_b128 v202, v[104:107] offset:1200
	s_waitcnt vmcnt(2)
	ds_write_b128 v202, v[108:111] offset:52480
	s_waitcnt vmcnt(1)
	ds_write_b128 v203, v[112:115] offset:1200
	s_waitcnt vmcnt(0)
	ds_write_b128 v203, v[116:119] offset:52480
.Lfill_done:
	s_cmp_eq_u32 s64, 31
	s_cbranch_scc1 .LBB0_845
	s_add_i32 s2, s10, 0x18000
	s_mov_b32 s3, s11
	s_lshl_b64 s[2:3], s[2:3], 1
	s_add_u32 s28, s0, s2
	s_addc_u32 s29, s1, s3
	s_add_u32 s2, s22, s2
	s_addc_u32 s3, s23, s3
	v_lshl_add_u64 v[96:97], s[28:29], 0, v[164:165]
	v_lshl_add_u64 v[100:101], s[2:3], 0, v[164:165]
	v_lshl_add_u64 v[104:105], s[28:29], 0, v[166:167]
	v_lshl_add_u64 v[108:109], s[2:3], 0, v[166:167]
	v_lshl_add_u64 v[112:113], s[28:29], 0, v[168:169]
	v_lshl_add_u64 v[116:117], s[2:3], 0, v[168:169]
	global_load_dwordx4 v[96:99], v[96:97], off
	s_nop 0
	global_load_dwordx4 v[100:103], v[100:101], off
	s_nop 0
	global_load_dwordx4 v[104:107], v[104:105], off
	s_nop 0
	global_load_dwordx4 v[108:111], v[108:109], off
	s_nop 0
	global_load_dwordx4 v[112:115], v[112:113], off
	s_nop 0
	global_load_dwordx4 v[116:119], v[116:117], off
